# GU unit scheduler: shift fast path when group size is 8 (skips generic udiv); SB walk ends exactly once all remaining weights round to bf16 zero (carry < 2^-136)
# speedup vs baseline: 1.0065x; 1.0065x over previous
;     __host__ __device__ bool next(int i, Unit& u) const {
;         const long L = (long)i * G + c; if (L >= nwg) return false;
;         int wgid = (int)L; { const int q = nwg / NXCD, r = nwg % NXCD, xcd = wgid % NXCD, off = wgid / NXCD; wgid = (xcd < r ? xcd * (q + 1) : r * (q + 1) + (xcd - r) * q) + off; }
;         const int nig = WGM * nN, gid = wgid / nig, fm = gid * WGM, gsz = (nM - fm) < WGM ? (nM - fm) : WGM;
;         u.pm = fm + ((wgid % nig) % gsz); u.pn = (wgid % nig) / gsz; return true;
;     }
.LBB0_183:
	s_add_i32 s69, s69, 1
	s_mul_i32 s0, s69, s25
	s_mul_hi_u32 s1, s69, s76
	s_add_i32 s1, s1, s0
	s_mul_i32 s0, s69, s76
	s_add_u32 s38, s0, s2
	s_addc_u32 s39, s1, s33
	v_mov_b64_e32 v[0:1], s[42:43]
	v_cmp_ge_i64_e32 vcc, s[38:39], v[0:1]
	v_cmp_lt_i64_e64 s[0:1], s[38:39], v[0:1]
	s_cbranch_vccnz .LBB0_185
	s_ashr_i32 s39, s38, 31
	s_lshr_b32 s39, s39, 29
	s_add_i32 s39, s38, s39
	s_ashr_i32 s56, s39, 3
	s_and_b32 s39, s39, -8
	s_sub_i32 s38, s38, s39
	s_cmp_lt_i32 s38, 0
	s_cselect_b32 s39, s37, s36
	s_mul_i32 s38, s39, s38
	s_add_i32 s38, s38, s56
	s_abs_i32 s56, s38
	s_mul_hi_u32 s57, s56, s60
	s_mul_i32 s70, s57, s58
	s_ashr_i32 s39, s38, 31
	s_sub_i32 s56, s56, s70
	s_xor_b32 s39, s39, s59
	s_add_i32 s70, s57, 1
	s_sub_i32 s71, s56, s58
	s_cmp_ge_u32 s56, s58
	s_cselect_b32 s57, s70, s57
	s_cselect_b32 s56, s71, s56
	s_add_i32 s70, s57, 1
	s_cmp_ge_u32 s56, s58
	s_cselect_b32 s56, s70, s57
	s_xor_b32 s56, s56, s39
	s_sub_i32 s39, s56, s39
	s_lshl_b32 s56, s39, 3
	s_sub_i32 s57, 0x80, s56
	s_min_i32 s57, s57, 8
	s_mul_i32 s39, s39, s48
	s_sub_i32 s38, s38, s39
	s_cmp_eq_u32 s57, 8
	s_cbranch_scc0 .Lsched_slow_gu
	s_lshr_b32 s70, s38, 3
	s_and_b32 s38, s38, 7
	s_add_i32 s71, s38, s56
	s_branch .LBB0_185
.Lsched_slow_gu:
	s_abs_i32 s70, s57
	v_cvt_f32_u32_e32 v0, s70
	s_sub_i32 s77, 0, s70
	v_rcp_iflag_f32_e32 v0, v0
	s_abs_i32 s71, s38
	s_xor_b32 s39, s38, s57
	s_ashr_i32 s39, s39, 31
	v_mul_f32_e32 v0, 0x4f7ffffe, v0
	v_cvt_u32_f32_e32 v0, v0
	s_nop 0
	v_readfirstlane_b32 s82, v0
	s_mul_i32 s77, s77, s82
	s_mul_hi_u32 s77, s82, s77
	s_add_i32 s82, s82, s77
	s_mul_hi_u32 s77, s71, s82
	s_mul_i32 s82, s77, s70
	s_sub_i32 s71, s71, s82
	s_add_i32 s82, s77, 1
	s_sub_i32 s84, s71, s70
	s_cmp_ge_u32 s71, s70
	s_cselect_b32 s77, s82, s77
	s_cselect_b32 s71, s84, s71
	s_add_i32 s82, s77, 1
	s_cmp_ge_u32 s71, s70
	s_cselect_b32 s70, s82, s77
	s_xor_b32 s70, s70, s39
	s_sub_i32 s70, s70, s39
	s_mul_i32 s39, s70, s57
	s_sub_i32 s38, s38, s39
	s_add_i32 s71, s38, s56

; __device__ __forceinline__ void sb_wave_unit(const bf16_t* Q, const bf16_t* K, const bf16_t* V, int ld, bf16_t* O, int ldo, int q0, char* wl, int lane) {
;     ...
;         if (j < 1 || !__any(carry > 0.f)) break;
.LBB0_634:
	v_mov_b32_e32 v64, v13
	v_mov_b32_e32 v65, v14
	v_mov_b32_e32 v66, v12
	v_mov_b32_e32 v67, v15
	v_pk_mul_f32 v[64:65], v[64:65], v[66:67]
	v_mov_b32_e32 v66, v17
	v_mov_b32_e32 v67, v18
	v_mov_b32_e32 v68, v16
	v_mov_b32_e32 v69, v19
	v_pk_mul_f32 v[66:67], v[66:67], v[68:69]
	v_mov_b32_e32 v68, v23
	v_mov_b32_e32 v69, v24
	v_mov_b32_e32 v70, v22
	v_mov_b32_e32 v71, v25
	v_mul_f32_e32 v64, v64, v65
	v_pk_mul_f32 v[68:69], v[68:69], v[70:71]
	v_mov_b32_e32 v70, v29
	v_mov_b32_e32 v71, v30
	v_mov_b32_e32 v72, v28
	v_mov_b32_e32 v73, v31
	v_pk_mul_f32 v[70:71], v[70:71], v[72:73]
	v_mov_b32_e32 v12, v64
	v_mov_b32_e32 v16, v64
	v_pk_mul_f32 v[70:71], v[70:71], v[70:71] op_sel:[0,1] op_sel_hi:[1,0]
	s_nop 0
	v_permlane32_swap_b32_e32 v12, v16
	v_cndmask_b32_e64 v65, v12, v16, s[40:41]
	v_mov_b32_e32 v12, v70
	v_mov_b32_e32 v16, v70
	s_nop 1
	v_permlane32_swap_b32_e32 v12, v16
	v_cndmask_b32_e64 v71, v12, v16, s[40:41]
	v_cndmask_b32_e64 v12, 1.0, v71, s[40:41]
	v_mul_f32_e32 v12, v237, v12
	v_mul_f32_e32 v16, v31, v12
	v_mul_f32_e32 v22, v30, v16
	v_mul_f32_e32 v28, v29, v22
	v_mul_f32_e32 v12, v27, v12
	v_mul_f32_e32 v22, v21, v22
	v_mul_f32_e32 v27, v20, v28
	v_mov_b32_e32 v20, v68
	v_mov_b32_e32 v21, v70
	v_mov_b32_e32 v70, v69
	v_pk_mul_f32 v[20:21], v[20:21], v[70:71]
	v_mul_f32_e32 v26, v26, v16
	v_mov_b32_e32 v16, v20
	v_mov_b32_e32 v28, v20
	s_nop 1
	v_permlane32_swap_b32_e32 v16, v28
	v_cndmask_b32_e64 v236, v16, v28, s[40:41]
	v_cndmask_b32_e64 v16, 1.0, v236, s[40:41]
	v_pk_mul_f32 v[20:21], v[20:21], v[236:237]
	s_add_i32 s77, s29, 8
	v_mul_f32_e32 v16, v16, v21
	v_mul_f32_e32 v25, v25, v16
	v_mul_f32_e32 v24, v24, v25
	v_mul_f32_e32 v23, v23, v24
	v_mul_f32_e32 v24, v9, v24
	v_mul_f32_e32 v23, v8, v23
	v_mov_b32_e32 v8, v66
	v_mov_b32_e32 v9, v20
	v_mov_b32_e32 v20, v67
	v_pk_mul_f32 v[8:9], v[8:9], v[20:21]
	v_mul_f32_e32 v11, v11, v16
	v_mov_b32_e32 v16, v8
	v_mov_b32_e32 v20, v8
	s_nop 1
	v_permlane32_swap_b32_e32 v16, v20
	v_cndmask_b32_e64 v16, v16, v20, s[40:41]
	v_mul_f32_e32 v8, v8, v16
	v_cndmask_b32_e64 v20, 1.0, v16, s[40:41]
	v_mul_f32_e32 v66, v8, v9
	v_cndmask_b32_e64 v8, 1.0, v65, s[40:41]
	v_mul_f32_e32 v20, v20, v9
	v_mul_f32_e32 v8, v8, v66
	v_mul_f32_e32 v19, v19, v20
	v_mul_f32_e32 v9, v15, v8
	v_mul_f32_e32 v18, v18, v19
	v_mul_f32_e32 v14, v14, v9
	v_mul_f32_e32 v17, v17, v18
	v_mul_f32_e32 v13, v13, v14
	v_mul_f32_e32 v10, v10, v25
	v_mul_f32_e32 v7, v7, v20
	v_mul_f32_e32 v6, v6, v19
	v_mul_f32_e32 v5, v5, v18
	v_mul_f32_e32 v4, v4, v17
	v_mul_f32_e32 v3, v3, v8
	v_mul_f32_e32 v2, v2, v9
	v_mul_f32_e32 v1, v1, v14
	v_mul_f32_e32 v0, v0, v13
	v_cvt_pk_bf16_f32 v16, v0, v1
	v_cvt_pk_bf16_f32 v17, v2, v3
	v_cvt_pk_bf16_f32 v18, v4, v5
	v_cvt_pk_bf16_f32 v19, v6, v7
	v_cvt_pk_bf16_f32 v68, v23, v24
	v_cvt_pk_bf16_f32 v69, v10, v11
	v_cvt_pk_bf16_f32 v70, v27, v22
	v_cvt_pk_bf16_f32 v71, v26, v12
	s_waitcnt lgkmcnt(0)
	ds_read_b64_tr_b16 v[0:1], v213
	ds_read_b64_tr_b16 v[2:3], v213 offset:512
	s_waitcnt lgkmcnt(0)
	v_mfma_f32_32x32x16_bf16 v[32:47], v[0:3], v[16:19], v[32:47]
	ds_read_b64_tr_b16 v[20:21], v213 offset:1024
	ds_read_b64_tr_b16 v[22:23], v213 offset:1536
	s_cmp_lt_i32 s77, 1
	s_nop 8
	v_mov_b64_e32 v[0:1], v[32:33]
	v_mov_b64_e32 v[2:3], v[34:35]
	v_mov_b64_e32 v[4:5], v[36:37]
	v_mov_b64_e32 v[6:7], v[38:39]
	v_mov_b64_e32 v[8:9], v[40:41]
	v_mov_b64_e32 v[10:11], v[42:43]
	v_mov_b64_e32 v[12:13], v[44:45]
	v_mov_b64_e32 v[14:15], v[46:47]
	s_waitcnt lgkmcnt(0)
	s_nop 0
	v_mfma_f32_32x32x16_bf16 v[0:15], v[20:23], v[68:71], v[0:15]
	ds_read_b64_tr_b16 v[20:21], v213 offset:2048
	ds_read_b64_tr_b16 v[22:23], v213 offset:2560
	ds_read_b64_tr_b16 v[32:33], v213 offset:3072
	ds_read_b64_tr_b16 v[34:35], v213 offset:3584
	s_waitcnt lgkmcnt(2)
	v_mfma_f32_32x32x16_bf16 v[48:63], v[20:23], v[16:19], v[48:63]
	s_nop 11
	v_mov_b64_e32 v[16:17], v[48:49]
	v_mov_b64_e32 v[18:19], v[50:51]
	v_mov_b64_e32 v[20:21], v[52:53]
	v_mov_b64_e32 v[22:23], v[54:55]
	v_mov_b64_e32 v[24:25], v[56:57]
	v_mov_b64_e32 v[26:27], v[58:59]
	v_mov_b64_e32 v[28:29], v[60:61]
	v_mov_b64_e32 v[30:31], v[62:63]
	s_waitcnt lgkmcnt(0)
	s_nop 0
	v_mfma_f32_32x32x16_bf16 v[16:31], v[32:35], v[68:71], v[16:31]
	s_cbranch_scc1 .LBB0_629
	v_mul_f32_e32 v32, v64, v65
	v_mul_f32_e32 v49, v32, v66
	v_cmp_lt_f32_e32 vcc, 0x2000, v49
	s_mov_b64 s[30:31], 0
	s_cbranch_vccz .LBB0_645
	s_add_i32 s1, s29, 5
	s_max_i32 s18, s1, 0
	s_lshl_b64 s[34:35], s[18:19], 5
	v_or_b32_e32 v32, s34, v212
	v_mad_u64_u32 v[32:33], s[42:43], v32, s78, v[228:229]
	v_mad_u32_u24 v33, s35, v242, v33
	global_load_dwordx4 v[124:127], v[32:33], off offset:2048
	global_load_dwordx4 v[120:123], v[32:33], off offset:2080
	global_load_dwordx4 v[116:119], v[32:33], off offset:2112
	global_load_dwordx4 v[112:115], v[32:33], off offset:2144
	v_or_b32_e32 v32, s34, v214
	v_mad_u64_u32 v[50:51], s[42:43], v32, s78, v[230:231]
	v_or_b32_e32 v48, s34, v216
	v_mad_u32_u24 v51, s35, v242, v51
	v_mad_u64_u32 v[52:53], s[42:43], v48, s78, v[230:231]
	v_or_b32_e32 v48, s34, v218
	v_mad_u32_u24 v53, s35, v242, v53
	global_load_dwordx4 v[132:135], v[50:51], off
	global_load_dwordx4 v[140:143], v[52:53], off
	v_mad_u64_u32 v[50:51], s[42:43], v48, s78, v[230:231]
	v_or_b32_e32 v48, s34, v220
	v_mad_u32_u24 v51, s35, v242, v51
	v_mad_u64_u32 v[52:53], s[42:43], v48, s78, v[230:231]
	v_mad_u32_u24 v53, s35, v242, v53
	global_load_dwordx4 v[152:155], v[50:51], off
	global_load_dwordx4 v[148:151], v[52:53], off
	v_mfma_f32_32x32x16_bf16 v[32:47], v[156:159], v[96:99], 0
	s_waitcnt lgkmcnt(0)
	s_add_i32 s0, s82, 0x100
	s_cmp_le_i32 s0, s39
	ds_write_b128 v211, v[164:167]
	ds_write_b128 v211, v[160:163] offset:512
	ds_write_b128 v211, v[172:175] offset:1024
	ds_write_b128 v211, v[168:171] offset:1536
	v_mfma_f32_32x32x16_bf16 v[32:47], v[144:147], v[100:103], v[32:47]
	v_mfma_f32_32x32x16_bf16 v[32:47], v[136:139], v[104:107], v[32:47]
	v_mfma_f32_32x32x16_bf16 v[32:47], v[128:131], v[108:111], v[32:47]
	s_nop 11
	v_mul_f32_e32 v44, 0xbe38aa3b, v44
	v_min_f32_e32 v44, 0x42c80000, v44
	v_mul_f32_e32 v32, 0xbe38aa3b, v32
	v_mul_f32_e32 v34, 0xbe38aa3b, v34
	v_mul_f32_e32 v36, 0xbe38aa3b, v36
	v_mul_f32_e32 v38, 0xbe38aa3b, v38
	v_mul_f32_e32 v40, 0xbe38aa3b, v40
	v_mul_f32_e32 v42, 0xbe38aa3b, v42
	v_exp_f32_e32 v66, v44
	v_mul_f32_e32 v44, 0xbe38aa3b, v45
	v_mul_f32_e32 v45, 0xbe38aa3b, v46
	v_min_f32_e32 v32, 0x42c80000, v32
	v_min_f32_e32 v34, 0x42c80000, v34
	v_min_f32_e32 v36, 0x42c80000, v36
	v_min_f32_e32 v38, 0x42c80000, v38
	v_min_f32_e32 v40, 0x42c80000, v40
	v_min_f32_e32 v42, 0x42c80000, v42
	v_min_f32_e32 v44, 0x42c80000, v44
	v_min_f32_e32 v45, 0x42c80000, v45
	v_exp_f32_e32 v50, v32
	v_mul_f32_e32 v32, 0xbe38aa3b, v33
	v_exp_f32_e32 v52, v34
	v_mul_f32_e32 v34, 0xbe38aa3b, v35
	v_exp_f32_e32 v56, v36
	v_mul_f32_e32 v36, 0xbe38aa3b, v37
	v_exp_f32_e32 v58, v38
	v_mul_f32_e32 v38, 0xbe38aa3b, v39
	v_exp_f32_e32 v62, v40
	v_mul_f32_e32 v40, 0xbe38aa3b, v41
	v_exp_f32_e32 v64, v42
	v_mul_f32_e32 v42, 0xbe38aa3b, v43
	v_exp_f32_e32 v67, v44
	v_exp_f32_e32 v68, v45
	v_mul_f32_e32 v45, 0xbe38aa3b, v47
	v_min_f32_e32 v32, 0x42c80000, v32
	v_min_f32_e32 v34, 0x42c80000, v34
	v_min_f32_e32 v36, 0x42c80000, v36
	v_min_f32_e32 v38, 0x42c80000, v38
	v_min_f32_e32 v40, 0x42c80000, v40
	v_min_f32_e32 v42, 0x42c80000, v42
	v_min_f32_e32 v45, 0x42c80000, v45
	v_exp_f32_e32 v51, v32
	v_exp_f32_e32 v53, v34
	v_exp_f32_e32 v57, v36
	v_exp_f32_e32 v59, v38
	v_exp_f32_e32 v63, v40
	v_exp_f32_e32 v65, v42
	v_exp_f32_e32 v69, v45
	v_add_f32_e32 v44, 1.0, v66
	v_rcp_f32_e32 v54, v44
	v_add_f32_e32 v44, 1.0, v67
	v_rcp_f32_e32 v55, v44
	v_add_f32_e32 v44, 1.0, v68
	v_add_f32_e32 v32, 1.0, v50
	v_add_f32_e32 v33, 1.0, v51
	v_add_f32_e32 v34, 1.0, v52
	v_add_f32_e32 v35, 1.0, v53
	v_add_f32_e32 v36, 1.0, v56
	v_add_f32_e32 v37, 1.0, v57
	v_add_f32_e32 v38, 1.0, v58
	v_add_f32_e32 v39, 1.0, v59
	v_add_f32_e32 v40, 1.0, v62
	v_add_f32_e32 v41, 1.0, v63
	v_add_f32_e32 v42, 1.0, v64
	v_add_f32_e32 v43, 1.0, v65
	v_rcp_f32_e32 v60, v44
	v_add_f32_e32 v44, 1.0, v69
	v_rcp_f32_e32 v32, v32
	v_rcp_f32_e32 v33, v33
	v_rcp_f32_e32 v34, v34
	v_rcp_f32_e32 v35, v35
	v_rcp_f32_e32 v36, v36
	v_rcp_f32_e32 v37, v37
	v_rcp_f32_e32 v38, v38
	v_rcp_f32_e32 v39, v39
	v_rcp_f32_e32 v40, v40
	v_rcp_f32_e32 v41, v41
	v_rcp_f32_e32 v42, v42
	v_rcp_f32_e32 v43, v43
	v_rcp_f32_e32 v61, v44
	v_pk_mul_f32 v[44:45], v[50:51], v[32:33]
	v_pk_mul_f32 v[46:47], v[52:53], v[34:35]
	v_pk_mul_f32 v[50:51], v[56:57], v[36:37]
	v_pk_mul_f32 v[52:53], v[58:59], v[38:39]
	v_pk_mul_f32 v[56:57], v[62:63], v[40:41]
	v_pk_mul_f32 v[58:59], v[64:65], v[42:43]
	v_pk_mul_f32 v[62:63], v[66:67], v[54:55]
	v_pk_mul_f32 v[64:65], v[68:69], v[60:61]
	s_cbranch_scc1 .LBB0_638
	v_add_u32_e32 v48, s48, v215
	v_add_u32_e32 v66, 0xe0, v48
	v_cmp_lt_i32_e32 vcc, v66, v234
	v_add_u32_e32 v66, 0xe1, v48
	v_cmp_lt_i32_e64 s[0:1], v66, v234
	v_add_u32_e32 v66, 0xe2, v48
	v_cmp_lt_i32_e64 s[42:43], v66, v234
	v_add_u32_e32 v66, 0xe3, v48
	v_cmp_lt_i32_e64 s[44:45], v66, v234
	v_add_u32_e32 v66, 0xe8, v48
	v_cmp_lt_i32_e64 s[50:51], v66, v234
	v_add_u32_e32 v66, 0xe9, v48
	v_cmp_lt_i32_e64 s[52:53], v66, v234
	v_add_u32_e32 v66, 0xea, v48
	v_cmp_lt_i32_e64 s[54:55], v66, v234
	v_add_u32_e32 v66, 0xeb, v48
	v_cmp_lt_i32_e64 s[56:57], v66, v234
	v_add_u32_e32 v66, 0xf0, v48
	v_cmp_lt_i32_e64 s[58:59], v66, v234
	v_add_u32_e32 v66, 0xf1, v48
	v_cmp_lt_i32_e64 s[60:61], v66, v234
	v_add_u32_e32 v66, 0xf2, v48
	v_cmp_lt_i32_e64 s[62:63], v66, v234
	v_add_u32_e32 v66, 0xf3, v48
	v_cmp_lt_i32_e64 s[64:65], v66, v234
	v_add_u32_e32 v66, 0xf8, v48
	v_cmp_lt_i32_e64 s[66:67], v66, v234
	v_add_u32_e32 v66, 0xf9, v48
	v_cmp_lt_i32_e64 s[68:69], v66, v234
	v_add_u32_e32 v66, 0xfa, v48
	v_add_u32_e32 v48, 0xfb, v48
	v_cmp_lt_i32_e64 s[70:71], v66, v234
	v_cmp_lt_i32_e64 s[72:73], v48, v234
	s_or_b64 s[70:71], s[72:73], s[70:71]
	s_or_b64 s[68:69], s[70:71], s[68:69]
	s_or_b64 s[66:67], s[68:69], s[66:67]
	s_or_b64 s[64:65], s[66:67], s[64:65]
	s_or_b64 s[62:63], s[64:65], s[62:63]
	s_or_b64 s[60:61], s[62:63], s[60:61]
	s_or_b64 s[58:59], s[60:61], s[58:59]
	s_or_b64 s[56:57], s[58:59], s[56:57]
	s_or_b64 s[54:55], s[56:57], s[54:55]
	s_or_b64 s[52:53], s[54:55], s[52:53]
	s_or_b64 s[50:51], s[52:53], s[50:51]
	s_or_b64 s[44:45], s[50:51], s[44:45]
	s_or_b64 s[42:43], s[44:45], s[42:43]
	s_or_b64 s[0:1], s[42:43], s[0:1]
	s_or_b64 vcc, s[0:1], vcc
	v_cndmask_b32_e64 v61, 0, v61, s[72:73]
	v_cndmask_b32_e64 v60, 0, v60, s[70:71]
	v_cndmask_b32_e64 v55, 0, v55, s[68:69]
	v_cndmask_b32_e64 v54, 0, v54, s[66:67]
	v_cndmask_b32_e64 v43, 0, v43, s[64:65]
	v_cndmask_b32_e64 v42, 0, v42, s[62:63]
	v_cndmask_b32_e64 v41, 0, v41, s[60:61]
	v_cndmask_b32_e64 v40, 0, v40, s[58:59]
	v_cndmask_b32_e64 v39, 0, v39, s[56:57]
	v_cndmask_b32_e64 v38, 0, v38, s[54:55]
	v_cndmask_b32_e64 v37, 0, v37, s[52:53]
	v_cndmask_b32_e64 v36, 0, v36, s[50:51]
	v_cndmask_b32_e64 v35, 0, v35, s[44:45]
	v_cndmask_b32_e64 v34, 0, v34, s[42:43]
	v_cndmask_b32_e64 v33, 0, v33, s[0:1]
	v_cndmask_b32_e32 v32, 0, v32, vcc
	v_cndmask_b32_e32 v44, 1.0, v44, vcc
	v_cndmask_b32_e64 v45, 1.0, v45, s[0:1]
	v_cndmask_b32_e64 v46, 1.0, v46, s[42:43]
	v_cndmask_b32_e64 v47, 1.0, v47, s[44:45]
	v_cndmask_b32_e64 v50, 1.0, v50, s[50:51]
	v_cndmask_b32_e64 v51, 1.0, v51, s[52:53]
	v_cndmask_b32_e64 v52, 1.0, v52, s[54:55]
	v_cndmask_b32_e64 v53, 1.0, v53, s[56:57]
	v_cndmask_b32_e64 v56, 1.0, v56, s[58:59]
	v_cndmask_b32_e64 v57, 1.0, v57, s[60:61]
	v_cndmask_b32_e64 v58, 1.0, v58, s[62:63]
	v_cndmask_b32_e64 v59, 1.0, v59, s[64:65]
	v_cndmask_b32_e64 v62, 1.0, v62, s[66:67]
	v_cndmask_b32_e64 v63, 1.0, v63, s[68:69]
	v_cndmask_b32_e64 v64, 1.0, v64, s[70:71]
	v_cndmask_b32_e64 v65, 1.0, v65, s[72:73]
.LBB0_638:
	v_mov_b32_e32 v66, v45
	v_mov_b32_e32 v67, v46
	v_mov_b32_e32 v68, v44
	v_mov_b32_e32 v69, v47
	v_pk_mul_f32 v[66:67], v[66:67], v[68:69]
	v_mov_b32_e32 v68, v50
	v_mul_f32_e32 v44, v66, v67
	v_mov_b32_e32 v66, v51
	v_mov_b32_e32 v67, v52
	v_mov_b32_e32 v69, v53
	v_pk_mul_f32 v[66:67], v[66:67], v[68:69]
	v_mov_b32_e32 v68, v57
	v_mov_b32_e32 v69, v58
	v_mov_b32_e32 v70, v56
	v_mov_b32_e32 v71, v59
	v_pk_mul_f32 v[68:69], v[68:69], v[70:71]
	v_mov_b32_e32 v70, v63
	v_mov_b32_e32 v71, v64
	v_mov_b32_e32 v72, v62
	v_mov_b32_e32 v73, v65
	v_pk_mul_f32 v[70:71], v[70:71], v[72:73]
	v_mov_b32_e32 v48, v44
	v_mov_b32_e32 v50, v44
	v_pk_mul_f32 v[70:71], v[70:71], v[70:71] op_sel:[0,1] op_sel_hi:[1,0]
	s_nop 0
	v_permlane32_swap_b32_e32 v48, v50
	v_cndmask_b32_e64 v50, v48, v50, s[40:41]
	v_mov_b32_e32 v48, v70
	v_mov_b32_e32 v56, v70
	s_nop 1
	v_permlane32_swap_b32_e32 v48, v56
	v_cndmask_b32_e64 v71, v48, v56, s[40:41]
	v_cndmask_b32_e64 v48, 1.0, v71, s[40:41]
	v_mul_f32_e32 v48, v49, v48
	v_mul_f32_e32 v56, v65, v48
	v_mul_f32_e32 v62, v64, v56
	v_mul_f32_e32 v63, v63, v62
	v_mul_f32_e32 v56, v60, v56
	v_mul_f32_e32 v60, v55, v62
	v_mul_f32_e32 v62, v54, v63
	v_mov_b32_e32 v54, v68
	v_mov_b32_e32 v55, v70
	v_mov_b32_e32 v70, v69
	v_pk_mul_f32 v[54:55], v[54:55], v[70:71]
	v_mul_f32_e32 v61, v61, v48
	v_mov_b32_e32 v48, v54
	v_mov_b32_e32 v63, v54
	s_nop 1
	v_permlane32_swap_b32_e32 v48, v63
	v_cndmask_b32_e64 v48, v48, v63, s[40:41]
	v_cndmask_b32_e64 v63, 1.0, v48, s[40:41]
	v_pk_mul_f32 v[48:49], v[54:55], v[48:49]
	s_mov_b64 s[44:45], -1
	v_mul_f32_e32 v54, v63, v49
	v_mul_f32_e32 v55, v59, v54
	v_mul_f32_e32 v58, v58, v55
	v_mul_f32_e32 v57, v57, v58
	v_mul_f32_e32 v43, v43, v54
	v_mul_f32_e32 v42, v42, v55
	v_mul_f32_e32 v54, v41, v58
	v_mul_f32_e32 v55, v40, v57
	v_mov_b32_e32 v40, v66
	v_mov_b32_e32 v41, v48
	v_mov_b32_e32 v48, v67
	v_pk_mul_f32 v[40:41], v[40:41], v[48:49]
	s_mov_b64 s[34:35], 0
	v_mov_b32_e32 v48, v40
	v_mov_b32_e32 v49, v40
	s_nop 1
	v_permlane32_swap_b32_e32 v48, v49
	v_cndmask_b32_e64 v48, v48, v49, s[40:41]
	v_cndmask_b32_e64 v49, 1.0, v48, s[40:41]
	v_mul_f32_e32 v49, v49, v41
	v_mul_f32_e32 v53, v53, v49
	v_mul_f32_e32 v52, v52, v53
	v_mul_f32_e32 v51, v51, v52
	v_mul_f32_e32 v39, v39, v49
	v_mul_f32_e32 v49, v36, v51
	v_mul_f32_e32 v36, v40, v48
	v_mul_f32_e32 v36, v36, v41
	v_cndmask_b32_e64 v40, 1.0, v50, s[40:41]
	v_mul_f32_e32 v40, v40, v36
	v_mul_f32_e32 v41, v47, v40
	v_mul_f32_e32 v46, v46, v41
	v_mul_f32_e32 v45, v45, v46
	v_mul_f32_e32 v38, v38, v53
	v_mul_f32_e32 v35, v35, v40
	v_mul_f32_e32 v34, v34, v41
	v_mul_f32_e32 v33, v33, v46
	v_mul_f32_e32 v32, v32, v45
	v_mul_f32_e32 v37, v37, v52
	v_cvt_pk_bf16_f32 v32, v32, v33
	v_cvt_pk_bf16_f32 v33, v34, v35
	v_cvt_pk_bf16_f32 v34, v49, v37
	v_cvt_pk_bf16_f32 v35, v38, v39
	v_cvt_pk_bf16_f32 v38, v55, v54
	v_cvt_pk_bf16_f32 v39, v42, v43
	v_cvt_pk_bf16_f32 v40, v62, v60
	v_cvt_pk_bf16_f32 v41, v56, v61
	s_waitcnt lgkmcnt(0)
	ds_read_b64_tr_b16 v[46:47], v213
	ds_read_b64_tr_b16 v[48:49], v213 offset:512
	ds_read_b64_tr_b16 v[52:53], v213 offset:1024
	ds_read_b64_tr_b16 v[54:55], v213 offset:1536
	s_waitcnt lgkmcnt(2)
	v_mfma_f32_32x32x16_bf16 v[64:79], v[46:49], v[32:35], v[0:15]
	s_cmp_eq_u32 s29, -7
	s_mov_b64 s[0:1], 0
	s_mov_b64 s[42:43], -1
	s_waitcnt lgkmcnt(0)
	v_mfma_f32_32x32x16_bf16 v[64:79], v[52:55], v[38:41], v[64:79]
	ds_read_b64_tr_b16 v[46:47], v213 offset:2048
	ds_read_b64_tr_b16 v[48:49], v213 offset:2560
	ds_read_b64_tr_b16 v[52:53], v213 offset:3072
	ds_read_b64_tr_b16 v[54:55], v213 offset:3584
	s_waitcnt lgkmcnt(2)
	v_mfma_f32_32x32x16_bf16 v[80:95], v[46:49], v[32:35], v[16:31]
	s_waitcnt lgkmcnt(0)
	v_mfma_f32_32x32x16_bf16 v[80:95], v[52:55], v[38:41], v[80:95]
	s_cbranch_scc1 .LBB0_631
; #define SBW_LOAD(j, KF, VR) do { const size_t kb_ = (size_t)(j) * 32; \
;         _Pragma("unroll") for (int s = 0; s < 4; ++s) KF[s] = *(const bf16x8*)(K + (kb_ + r32) * ld + s * 16 + hi * 8); \
;         _Pragma("unroll") for (int c4 = 0; c4 < 4; ++c4) VR[c4] = *(const u32x4*)(V + (kb_ + (lane >> 3) + 8 * c4) * ld + (lane & 7) * 8); } while (0)
; __device__ __forceinline__ void sb_wave_unit(const bf16_t* Q, const bf16_t* K, const bf16_t* V, int ld, bf16_t* O, int ldo, int q0, char* wl, int lane) {
;     ...
;         if (j < 2 || !__any(carry > 0.f)) break;
;         SBW_LOAD(SBW_CL(j - 4), kfB, vrB);
;         SBW_TILE(j - 2, kfC, vrC);
	v_mul_f32_e32 v32, v44, v50
	v_mul_f32_e32 v49, v32, v36
	v_cmp_lt_f32_e32 vcc, 0x2000, v49
	s_cbranch_vccz .LBB0_646
	s_min_u32 s0, s28, 4
	s_sub_i32 s0, s29, s0
	s_add_i32 s18, s0, 8
	s_lshl_b64 s[0:1], s[18:19], 5
	v_or_b32_e32 v32, s0, v212
	v_mad_u64_u32 v[32:33], s[42:43], v32, s78, v[228:229]
	v_mad_u32_u24 v33, s1, v242, v33
	global_load_dwordx4 v[156:159], v[32:33], off offset:2048
	global_load_dwordx4 v[144:147], v[32:33], off offset:2080
	global_load_dwordx4 v[136:139], v[32:33], off offset:2112
	global_load_dwordx4 v[128:131], v[32:33], off offset:2144
	v_or_b32_e32 v32, s0, v214
	v_mad_u64_u32 v[50:51], s[42:43], v32, s78, v[230:231]
	v_or_b32_e32 v48, s0, v216
	v_mad_u32_u24 v51, s1, v242, v51
	v_mad_u64_u32 v[52:53], s[42:43], v48, s78, v[230:231]
	v_or_b32_e32 v48, s0, v218
	v_mad_u32_u24 v53, s1, v242, v53
	global_load_dwordx4 v[164:167], v[50:51], off
	global_load_dwordx4 v[160:163], v[52:53], off
	v_mad_u64_u32 v[50:51], s[42:43], v48, s78, v[230:231]
	v_or_b32_e32 v48, s0, v220
	v_mad_u32_u24 v51, s1, v242, v51
	v_mad_u64_u32 v[52:53], s[42:43], v48, s78, v[230:231]
	v_mad_u32_u24 v53, s1, v242, v53
	global_load_dwordx4 v[172:175], v[50:51], off
	global_load_dwordx4 v[168:171], v[52:53], off
	v_mfma_f32_32x32x16_bf16 v[32:47], v[188:191], v[96:99], 0
	s_waitcnt lgkmcnt(0)
	s_addk_i32 s82, 0xdf
	s_cmp_lt_i32 s82, s39
	ds_write_b128 v211, v[192:195]
	ds_write_b128 v211, v[196:199] offset:512
	ds_write_b128 v211, v[204:207] offset:1024
	ds_write_b128 v211, v[200:203] offset:1536
	v_mfma_f32_32x32x16_bf16 v[32:47], v[184:187], v[100:103], v[32:47]
	v_mfma_f32_32x32x16_bf16 v[32:47], v[180:183], v[104:107], v[32:47]
	v_mfma_f32_32x32x16_bf16 v[32:47], v[176:179], v[108:111], v[32:47]
	s_nop 11
	v_mul_f32_e32 v44, 0xbe38aa3b, v44
	v_min_f32_e32 v44, 0x42c80000, v44
	v_mul_f32_e32 v32, 0xbe38aa3b, v32
	v_mul_f32_e32 v34, 0xbe38aa3b, v34
	v_mul_f32_e32 v36, 0xbe38aa3b, v36
	v_mul_f32_e32 v38, 0xbe38aa3b, v38
	v_mul_f32_e32 v40, 0xbe38aa3b, v40
	v_mul_f32_e32 v42, 0xbe38aa3b, v42
	v_exp_f32_e32 v178, v44
	v_mul_f32_e32 v44, 0xbe38aa3b, v45
	v_mul_f32_e32 v45, 0xbe38aa3b, v46
	v_min_f32_e32 v32, 0x42c80000, v32
	v_min_f32_e32 v34, 0x42c80000, v34
	v_min_f32_e32 v36, 0x42c80000, v36
	v_min_f32_e32 v38, 0x42c80000, v38
	v_min_f32_e32 v40, 0x42c80000, v40
	v_min_f32_e32 v42, 0x42c80000, v42
	v_min_f32_e32 v44, 0x42c80000, v44
	v_min_f32_e32 v45, 0x42c80000, v45
	v_exp_f32_e32 v50, v32
	v_mul_f32_e32 v32, 0xbe38aa3b, v33
	v_exp_f32_e32 v52, v34
	v_mul_f32_e32 v34, 0xbe38aa3b, v35
	v_exp_f32_e32 v56, v36
	v_mul_f32_e32 v36, 0xbe38aa3b, v37
	v_exp_f32_e32 v58, v38
	v_mul_f32_e32 v38, 0xbe38aa3b, v39
	v_exp_f32_e32 v62, v40
	v_mul_f32_e32 v40, 0xbe38aa3b, v41
	v_exp_f32_e32 v176, v42
	v_mul_f32_e32 v42, 0xbe38aa3b, v43
	v_exp_f32_e32 v179, v44
	v_exp_f32_e32 v180, v45
	v_mul_f32_e32 v45, 0xbe38aa3b, v47
	v_min_f32_e32 v32, 0x42c80000, v32
	v_min_f32_e32 v34, 0x42c80000, v34
	v_min_f32_e32 v36, 0x42c80000, v36
	v_min_f32_e32 v38, 0x42c80000, v38
	v_min_f32_e32 v40, 0x42c80000, v40
	v_min_f32_e32 v42, 0x42c80000, v42
	v_min_f32_e32 v45, 0x42c80000, v45
	v_exp_f32_e32 v51, v32
	v_exp_f32_e32 v53, v34
	v_exp_f32_e32 v57, v36
	v_exp_f32_e32 v59, v38
	v_exp_f32_e32 v63, v40
	v_exp_f32_e32 v177, v42
	v_exp_f32_e32 v181, v45
	v_add_f32_e32 v44, 1.0, v178
	v_rcp_f32_e32 v54, v44
	v_add_f32_e32 v44, 1.0, v179
	v_rcp_f32_e32 v55, v44
	v_add_f32_e32 v44, 1.0, v180
	v_add_f32_e32 v32, 1.0, v50
	v_add_f32_e32 v33, 1.0, v51
	v_add_f32_e32 v34, 1.0, v52
	v_add_f32_e32 v35, 1.0, v53
	v_add_f32_e32 v36, 1.0, v56
	v_add_f32_e32 v37, 1.0, v57
	v_add_f32_e32 v38, 1.0, v58
	v_add_f32_e32 v39, 1.0, v59
	v_add_f32_e32 v40, 1.0, v62
	v_add_f32_e32 v41, 1.0, v63
	v_add_f32_e32 v42, 1.0, v176
	v_add_f32_e32 v43, 1.0, v177
	v_rcp_f32_e32 v60, v44
	v_add_f32_e32 v44, 1.0, v181
	v_rcp_f32_e32 v32, v32
	v_rcp_f32_e32 v33, v33
	v_rcp_f32_e32 v34, v34
	v_rcp_f32_e32 v35, v35
	v_rcp_f32_e32 v36, v36
	v_rcp_f32_e32 v37, v37
	v_rcp_f32_e32 v38, v38
	v_rcp_f32_e32 v39, v39
	v_rcp_f32_e32 v40, v40
	v_rcp_f32_e32 v41, v41
	v_rcp_f32_e32 v42, v42
	v_rcp_f32_e32 v43, v43
	v_rcp_f32_e32 v61, v44
	v_pk_mul_f32 v[44:45], v[50:51], v[32:33]
	v_pk_mul_f32 v[46:47], v[52:53], v[34:35]
	v_pk_mul_f32 v[50:51], v[56:57], v[36:37]
	v_pk_mul_f32 v[52:53], v[58:59], v[38:39]
	v_pk_mul_f32 v[56:57], v[62:63], v[40:41]
	v_pk_mul_f32 v[58:59], v[176:177], v[42:43]
	v_pk_mul_f32 v[62:63], v[178:179], v[54:55]
	v_pk_mul_f32 v[176:177], v[180:181], v[60:61]
	s_cbranch_scc1 .LBB0_642
	v_add_u32_e32 v48, s48, v215
	v_add_u32_e32 v178, 0xc0, v48
	v_cmp_lt_i32_e32 vcc, v178, v234
	v_add_u32_e32 v178, 0xc1, v48
	v_cmp_lt_i32_e64 s[0:1], v178, v234
	v_add_u32_e32 v178, 0xc2, v48
	v_cmp_lt_i32_e64 s[42:43], v178, v234
	v_add_u32_e32 v178, 0xc3, v48
	v_cmp_lt_i32_e64 s[44:45], v178, v234
	v_add_u32_e32 v178, 0xc8, v48
	v_cmp_lt_i32_e64 s[50:51], v178, v234
	v_add_u32_e32 v178, 0xc9, v48
	v_cmp_lt_i32_e64 s[52:53], v178, v234
	v_add_u32_e32 v178, 0xca, v48
	v_cmp_lt_i32_e64 s[54:55], v178, v234
	v_add_u32_e32 v178, 0xcb, v48
	v_cmp_lt_i32_e64 s[56:57], v178, v234
	v_add_u32_e32 v178, 0xd0, v48
	v_cmp_lt_i32_e64 s[58:59], v178, v234
	v_add_u32_e32 v178, 0xd1, v48
	v_cmp_lt_i32_e64 s[60:61], v178, v234
	v_add_u32_e32 v178, 0xd2, v48
	v_cmp_lt_i32_e64 s[62:63], v178, v234
	v_add_u32_e32 v178, 0xd3, v48
	v_cmp_lt_i32_e64 s[64:65], v178, v234
	v_add_u32_e32 v178, 0xd8, v48
	v_cmp_lt_i32_e64 s[66:67], v178, v234
	v_add_u32_e32 v178, 0xd9, v48
	v_cmp_lt_i32_e64 s[68:69], v178, v234
	v_add_u32_e32 v178, 0xda, v48
	v_add_u32_e32 v48, 0xdb, v48
	v_cmp_lt_i32_e64 s[70:71], v178, v234
	v_cmp_lt_i32_e64 s[72:73], v48, v234
	s_or_b64 s[70:71], s[72:73], s[70:71]
	s_or_b64 s[68:69], s[70:71], s[68:69]
	s_or_b64 s[66:67], s[68:69], s[66:67]
	s_or_b64 s[64:65], s[66:67], s[64:65]
	s_or_b64 s[62:63], s[64:65], s[62:63]
	s_or_b64 s[60:61], s[62:63], s[60:61]
	s_or_b64 s[58:59], s[60:61], s[58:59]
	s_or_b64 s[56:57], s[58:59], s[56:57]
	s_or_b64 s[54:55], s[56:57], s[54:55]
	s_or_b64 s[52:53], s[54:55], s[52:53]
	s_or_b64 s[50:51], s[52:53], s[50:51]
	s_or_b64 s[44:45], s[50:51], s[44:45]
	s_or_b64 s[42:43], s[44:45], s[42:43]
	s_or_b64 s[0:1], s[42:43], s[0:1]
	s_or_b64 vcc, s[0:1], vcc
	v_cndmask_b32_e64 v61, 0, v61, s[72:73]
	v_cndmask_b32_e64 v60, 0, v60, s[70:71]
	v_cndmask_b32_e64 v55, 0, v55, s[68:69]
	v_cndmask_b32_e64 v54, 0, v54, s[66:67]
	v_cndmask_b32_e64 v43, 0, v43, s[64:65]
	v_cndmask_b32_e64 v42, 0, v42, s[62:63]
	v_cndmask_b32_e64 v41, 0, v41, s[60:61]
	v_cndmask_b32_e64 v40, 0, v40, s[58:59]
	v_cndmask_b32_e64 v39, 0, v39, s[56:57]
	v_cndmask_b32_e64 v38, 0, v38, s[54:55]
	v_cndmask_b32_e64 v37, 0, v37, s[52:53]
	v_cndmask_b32_e64 v36, 0, v36, s[50:51]
	v_cndmask_b32_e64 v35, 0, v35, s[44:45]
	v_cndmask_b32_e64 v34, 0, v34, s[42:43]
	v_cndmask_b32_e64 v33, 0, v33, s[0:1]
	v_cndmask_b32_e32 v32, 0, v32, vcc
	v_cndmask_b32_e32 v44, 1.0, v44, vcc
	v_cndmask_b32_e64 v45, 1.0, v45, s[0:1]
	v_cndmask_b32_e64 v46, 1.0, v46, s[42:43]
	v_cndmask_b32_e64 v47, 1.0, v47, s[44:45]
	v_cndmask_b32_e64 v50, 1.0, v50, s[50:51]
	v_cndmask_b32_e64 v51, 1.0, v51, s[52:53]
	v_cndmask_b32_e64 v52, 1.0, v52, s[54:55]
	v_cndmask_b32_e64 v53, 1.0, v53, s[56:57]
	v_cndmask_b32_e64 v56, 1.0, v56, s[58:59]
	v_cndmask_b32_e64 v57, 1.0, v57, s[60:61]
	v_cndmask_b32_e64 v58, 1.0, v58, s[62:63]
	v_cndmask_b32_e64 v59, 1.0, v59, s[64:65]
	v_cndmask_b32_e64 v62, 1.0, v62, s[66:67]
	v_cndmask_b32_e64 v63, 1.0, v63, s[68:69]
	v_cndmask_b32_e64 v176, 1.0, v176, s[70:71]
	v_cndmask_b32_e64 v177, 1.0, v177, s[72:73]
; __device__ __forceinline__ void sb_wave_unit(const bf16_t* Q, const bf16_t* K, const bf16_t* V, int ld, bf16_t* O, int ldo, int q0, char* wl, int lane) {
;     ...
;         if (j < 3 || !__any(carry > 0.f)) break;
;         j -= 3;
.LBB0_642:
	v_mov_b32_e32 v178, v45
	v_mov_b32_e32 v179, v46
	v_mov_b32_e32 v180, v44
	v_mov_b32_e32 v181, v47
	v_pk_mul_f32 v[178:179], v[178:179], v[180:181]
	v_mov_b32_e32 v180, v51
	v_mov_b32_e32 v181, v52
	v_mov_b32_e32 v182, v50
	v_mov_b32_e32 v183, v53
	v_pk_mul_f32 v[180:181], v[180:181], v[182:183]
	v_mov_b32_e32 v182, v57
	v_mov_b32_e32 v183, v58
	v_mov_b32_e32 v184, v56
	v_mov_b32_e32 v185, v59
	v_mul_f32_e32 v178, v178, v179
	v_pk_mul_f32 v[182:183], v[182:183], v[184:185]
	v_mov_b32_e32 v184, v63
	v_mov_b32_e32 v185, v176
	v_mov_b32_e32 v186, v62
	v_mov_b32_e32 v187, v177
	v_pk_mul_f32 v[184:185], v[184:185], v[186:187]
	v_mov_b32_e32 v44, v178
	v_mov_b32_e32 v48, v178
	v_pk_mul_f32 v[184:185], v[184:185], v[184:185] op_sel:[0,1] op_sel_hi:[1,0]
	s_nop 0
	v_permlane32_swap_b32_e32 v44, v48
	v_cndmask_b32_e64 v179, v44, v48, s[40:41]
	v_mov_b32_e32 v44, v184
	v_mov_b32_e32 v48, v184
	s_nop 1
	v_permlane32_swap_b32_e32 v44, v48
	v_cndmask_b32_e64 v185, v44, v48, s[40:41]
	v_cndmask_b32_e64 v44, 1.0, v185, s[40:41]
	v_mul_f32_e32 v44, v49, v44
	v_mul_f32_e32 v48, v177, v44
	v_mul_f32_e32 v50, v176, v48
	v_mul_f32_e32 v56, v63, v50
	v_mul_f32_e32 v50, v55, v50
	v_mul_f32_e32 v56, v54, v56
	v_mov_b32_e32 v54, v182
	v_mov_b32_e32 v55, v184
	v_mov_b32_e32 v184, v183
	v_pk_mul_f32 v[54:55], v[54:55], v[184:185]
	v_mul_f32_e32 v44, v61, v44
	v_mul_f32_e32 v60, v60, v48
	v_mov_b32_e32 v48, v54
	v_mov_b32_e32 v61, v54
	s_nop 1
	v_permlane32_swap_b32_e32 v48, v61
	v_cndmask_b32_e64 v48, v48, v61, s[40:41]
	v_cndmask_b32_e64 v61, 1.0, v48, s[40:41]
	v_pk_mul_f32 v[48:49], v[54:55], v[48:49]
	s_cmp_lt_u32 s77, 3
	v_mul_f32_e32 v54, v61, v49
	v_mul_f32_e32 v55, v59, v54
	v_mul_f32_e32 v58, v58, v55
	v_mul_f32_e32 v57, v57, v58
	v_mul_f32_e32 v43, v43, v54
	v_mul_f32_e32 v42, v42, v55
	v_mul_f32_e32 v54, v41, v58
	v_mul_f32_e32 v55, v40, v57
	v_mov_b32_e32 v40, v180
	v_mov_b32_e32 v41, v48
	v_mov_b32_e32 v48, v181
	v_pk_mul_f32 v[40:41], v[40:41], v[48:49]
	s_mov_b64 s[42:43], -1
	v_mov_b32_e32 v48, v40
	v_mov_b32_e32 v49, v40
	s_nop 1
	v_permlane32_swap_b32_e32 v48, v49
	v_cndmask_b32_e64 v48, v48, v49, s[40:41]
	v_mul_f32_e32 v40, v40, v48
	v_cndmask_b32_e64 v49, 1.0, v48, s[40:41]
	v_mul_f32_e32 v176, v40, v41
	v_cndmask_b32_e64 v40, 1.0, v179, s[40:41]
	v_mul_f32_e32 v49, v49, v41
	v_mul_f32_e32 v40, v40, v176
	v_mul_f32_e32 v53, v53, v49
	v_mul_f32_e32 v41, v47, v40
	v_mul_f32_e32 v52, v52, v53
	v_mul_f32_e32 v46, v46, v41
	v_mul_f32_e32 v51, v51, v52
	v_mul_f32_e32 v45, v45, v46
	v_mul_f32_e32 v39, v39, v49
	v_mul_f32_e32 v38, v38, v53
	v_mul_f32_e32 v37, v37, v52
	v_mul_f32_e32 v36, v36, v51
	v_mul_f32_e32 v35, v35, v40
	v_mul_f32_e32 v34, v34, v41
	v_mul_f32_e32 v33, v33, v46
	v_mul_f32_e32 v32, v32, v45
	v_cvt_pk_bf16_f32 v180, v32, v33
	v_cvt_pk_bf16_f32 v181, v34, v35
	v_cvt_pk_bf16_f32 v182, v36, v37
	v_cvt_pk_bf16_f32 v183, v38, v39
	v_cvt_pk_bf16_f32 v184, v55, v54
	v_cvt_pk_bf16_f32 v185, v42, v43
	v_cvt_pk_bf16_f32 v186, v56, v50
	v_cvt_pk_bf16_f32 v187, v60, v44
	s_waitcnt lgkmcnt(0)
	ds_read_b64_tr_b16 v[48:49], v213
	ds_read_b64_tr_b16 v[50:51], v213 offset:512
	ds_read_b64_tr_b16 v[52:53], v213 offset:1024
	ds_read_b64_tr_b16 v[54:55], v213 offset:1536
	s_waitcnt lgkmcnt(2)
	v_mfma_f32_32x32x16_bf16 v[32:47], v[48:51], v[180:183], v[64:79]
	ds_read_b64_tr_b16 v[188:189], v213 offset:2048
	ds_read_b64_tr_b16 v[190:191], v213 offset:2560
	ds_read_b64_tr_b16 v[192:193], v213 offset:3072
	ds_read_b64_tr_b16 v[194:195], v213 offset:3584
	s_waitcnt lgkmcnt(4)
	v_mfma_f32_32x32x16_bf16 v[32:47], v[52:55], v[184:187], v[32:47]
	s_waitcnt lgkmcnt(2)
	v_mfma_f32_32x32x16_bf16 v[48:63], v[188:191], v[180:183], v[80:95]
	s_waitcnt lgkmcnt(0)
	v_mfma_f32_32x32x16_bf16 v[48:63], v[192:195], v[184:187], v[48:63]
	s_cbranch_scc1 .LBB0_644
	v_mul_f32_e32 v177, v178, v179
	v_mul_f32_e32 v237, v177, v176
	s_addk_i32 s48, 0xffa0
	s_add_i32 s28, s28, -3
	v_cmp_lt_f32_e32 vcc, 0x2000, v237
	s_cmp_eq_u64 vcc, 0
	s_cselect_b64 s[42:43], -1, 0
